# attention queues per batch / per XCD when the placement flag is set (same unit numbering, counters in spare barrier words) so that every grid barrier after the first is XCD-local
# speedup vs baseline: 1.0553x; 1.0373x over previous
; template <int Q>
; DI void attn_queue(const Params& p, int l, char* smem, int* s_unit, int cb) {
;     const bool ctxu = l < DEPTH - 1;
;     const int total = (Q == 0) ? (ctxu ? 576 : 512) : (Q == 1) ? (ctxu ? 960 : 768) : 768;
;     for (;;) {
;         if (threadIdx.x == 0) *s_unit = (int)atomicAdd(p.ctr + cb + l * 4 + Q, 1u);
;         __syncthreads();
;         const int u = *s_unit;
;         __syncthreads();
;         if (u >= total) break;
;         if (Q == 0) {
;             int b, head, qt, t1 = 0, n1 = 36;
;             if (u < 512) { b = u >> 6; head = (u >> 4) & 3; qt = u & 15; }
;             else { const int v = u - 512; b = v >> 3; head = (v >> 1) & 3; qt = 16 + (v & 1); t1 = 32; n1 = 4; }
;             attn_unit<0>(p, l, b, head, qt, head * 64, 256 + head * 64, head * 64, 768 + head * 64, head * 64, t1, n1, 0, 0, smem);
.LBB0_72:
	s_and_saveexec_b64 s[4:5], s[54:55]
	s_cbranch_execz .LBB0_76
	s_mov_b64 s[8:9], exec
	v_mbcnt_lo_u32_b32 v0, s8, 0
	v_mbcnt_hi_u32_b32 v0, s9, v0
	v_cmp_eq_u32_e32 vcc, 0, v0
	s_and_saveexec_b64 s[6:7], vcc
	s_cbranch_execz .LBB0_75
	ds_read_b32 v2, v193 offset:8
	s_load_dwordx2 s[34:35], s[0:1], 0x100
	s_lshl_b64 s[40:41], s[48:49], 2
	s_waitcnt lgkmcnt(0)
	s_add_u32 s34, s34, s40
	s_addc_u32 s35, s35, s41
	v_readfirstlane_b32 s40, v2
	s_nop 0
	s_cmp_eq_u32 s40, 0
	s_cbranch_scc1 .Lq0_glob
	v_readlane_b32 s8, v254, 0
	s_nop 0
	s_and_b32 s8, s8, 7
	s_lshl_b32 s9, s8, 8
	s_lshl_b32 s40, s60, 4
	s_add_i32 s9, s9, s40
	s_addk_i32 s9, 0x2420
	s_add_u32 s34, s68, s9
	s_addc_u32 s35, s69, 0
	v_mov_b32_e32 v1, 1
	global_atomic_add v1, v193, v1, s[34:35] sc0
	s_waitcnt vmcnt(0)
	v_readfirstlane_b32 s9, v1
	s_nop 0
	s_lshr_b32 s40, s28, 3
	s_lshl_b32 s34, s8, 6
	s_add_i32 s34, s34, s9
	s_lshl_b32 s35, s8, 3
	s_add_i32 s35, s35, s9
	s_addk_i32 s35, 0x1c0
	s_cmp_lt_u32 s9, 64
	s_cselect_b32 s34, s34, s35
	s_cmp_lt_u32 s9, s40
	s_cselect_b32 s34, s34, s28
	v_mov_b32_e32 v1, s34
	s_branch .LBB0_75
.Lq0_glob:
	s_bcnt1_i32_b64 s8, s[8:9]
	v_mov_b32_e32 v1, s8
	global_atomic_add v1, v193, v1, s[34:35] sc0

; template <int Q>
; DI void attn_queue(const Params& p, int l, char* smem, int* s_unit, int cb) {
;     ...
;         } else if (Q == 1) {
;             int b, head, qt, t1 = 0, n1 = 36; bool cgrp = false;
;             if (u < 768) { b = u / 96; head = (u >> 4) % 6; qt = u & 15; }
;             else if (u < 864) { const int v = u - 768; b = v / 12; head = (v >> 1) % 6; qt = 16 + (v & 1); t1 = 32; n1 = 4; }
;             else { const int v = u - 864; b = v / 12; head = (v >> 1) % 6; qt = 16 + (v & 1); t1 = 32; n1 = 4; cgrp = true; }
;             int qcol, kcol, vfeat, gcol, mixcol;
;             if (!cgrp) { const int kv = head / 3; qcol = 1024 + head * 64; kcol = 1408 + kv * 64; vfeat = 256 + kv * 64; gcol = 1664 + head * 64; mixcol = 256 + head * 64; }
;             else { qcol = 2048 + head * 64; kcol = 2432 + head * 64; vfeat = 384 + head * 64; gcol = 3200 + head * 64; mixcol = 640 + head * 64; }
;             attn_unit<1>(p, l, b, head, qt, qcol, kcol, vfeat, gcol, mixcol, t1, n1, 0, 0, smem);
.LBB0_86:
	s_and_saveexec_b64 s[4:5], s[54:55]
	s_cbranch_execz .LBB0_90
	s_mov_b64 s[8:9], exec
	v_mbcnt_lo_u32_b32 v0, s8, 0
	v_mbcnt_hi_u32_b32 v0, s9, v0
	v_cmp_eq_u32_e32 vcc, 0, v0
	s_and_saveexec_b64 s[6:7], vcc
	s_cbranch_execz .LBB0_89
	ds_read_b32 v2, v193 offset:8
	s_load_dwordx2 s[34:35], s[0:1], 0x100
	s_lshl_b64 s[40:41], s[48:49], 2
	s_waitcnt lgkmcnt(0)
	s_add_u32 s34, s34, s40
	s_addc_u32 s35, s35, s41
	v_readfirstlane_b32 s40, v2
	s_nop 0
	s_cmp_eq_u32 s40, 0
	s_cbranch_scc1 .Lq1_glob
	v_readlane_b32 s8, v254, 0
	s_nop 0
	s_and_b32 s8, s8, 7
	s_lshl_b32 s9, s8, 8
	s_lshl_b32 s40, s60, 4
	s_add_i32 s9, s9, s40
	s_addk_i32 s9, 0x2424
	s_add_u32 s34, s68, s9
	s_addc_u32 s35, s69, 0
	v_mov_b32_e32 v1, 1
	global_atomic_add v1, v193, v1, s[34:35] sc0
	s_waitcnt vmcnt(0)
	v_readfirstlane_b32 s9, v1
	s_nop 0
	s_lshr_b32 s40, s28, 3
	s_mul_i32 s35, s8, 12
	s_add_i32 s35, s35, s9
	s_mul_i32 s34, s8, 0x60
	s_add_i32 s34, s34, s9
	s_add_i32 s8, s35, 0x2a0
	s_cmp_lt_u32 s9, 0x60
	s_cselect_b32 s34, s34, s8
	s_add_i32 s8, s35, 0x2f4
	s_cmp_lt_u32 s9, 0x6c
	s_cselect_b32 s34, s34, s8
	s_cmp_lt_u32 s9, s40
	s_cselect_b32 s34, s34, s28
	v_mov_b32_e32 v1, s34
	s_branch .LBB0_89
.Lq1_glob:
	s_bcnt1_i32_b64 s8, s[8:9]
	v_mov_b32_e32 v1, s8
	global_atomic_add v1, v193, v1, s[34:35] offset:4 sc0

; template <int Q>
; DI void attn_queue(const Params& p, int l, char* smem, int* s_unit, int cb) {
;     ...
;         } else {
;             const int b = u / 96, head = (u >> 4) % 6, qt = u & 15;
;             const int t1 = min(max(2 * qt - 4, 0), 24), n1 = min(max(2 * qt + 1 - 4, 0), 24) + 8 - t1;
;             attn_unit<2>(p, l, b, head, qt, 2048 + head * 64, 2432 + head * 64, 384 + head * 64, 3200 + head * 64, 640 + head * 64, t1, n1, 32, 4, smem);
;         }
.LBB0_109:
	s_and_saveexec_b64 s[4:5], s[54:55]
	s_cbranch_execz .LBB0_113
	s_mov_b64 s[8:9], exec
	v_mbcnt_lo_u32_b32 v0, s8, 0
	v_mbcnt_hi_u32_b32 v0, s9, v0
	v_cmp_eq_u32_e32 vcc, 0, v0
	s_and_saveexec_b64 s[6:7], vcc
	s_cbranch_execz .LBB0_112
	ds_read_b32 v2, v193 offset:8
	s_load_dwordx2 s[28:29], s[0:1], 0x100
	s_lshl_b64 s[34:35], s[48:49], 2
	s_waitcnt lgkmcnt(0)
	s_add_u32 s28, s28, s34
	s_addc_u32 s29, s29, s35
	v_readfirstlane_b32 s34, v2
	s_nop 0
	s_cmp_eq_u32 s34, 0
	s_cbranch_scc1 .Lq2_glob
	v_readlane_b32 s8, v254, 0
	s_nop 0
	s_and_b32 s8, s8, 7
	s_lshl_b32 s9, s8, 8
	s_lshl_b32 s34, s60, 4
	s_add_i32 s9, s9, s34
	s_addk_i32 s9, 0x2428
	s_add_u32 s28, s68, s9
	s_addc_u32 s29, s69, 0
	v_mov_b32_e32 v1, 1
	global_atomic_add v1, v193, v1, s[28:29] sc0
	s_waitcnt vmcnt(0)
	v_readfirstlane_b32 s9, v1
	s_nop 0
	s_mul_i32 s28, s8, 0x60
	s_add_i32 s28, s28, s9
	s_cmp_lt_u32 s9, 0x60
	s_cselect_b32 s28, s28, 0x300
	v_mov_b32_e32 v1, s28
	s_branch .LBB0_112
.Lq2_glob:
	s_bcnt1_i32_b64 s8, s[8:9]
	v_mov_b32_e32 v1, s8
	global_atomic_add v1, v193, v1, s[28:29] offset:8 sc0

; DI unsigned xb_ld(unsigned* p)              { return __hip_atomic_load(p, __ATOMIC_RELAXED, __HIP_MEMORY_SCOPE_AGENT); }
; DI unsigned xb_add(unsigned* p, unsigned v) { return __hip_atomic_fetch_add(p, v, __ATOMIC_RELAXED, __HIP_MEMORY_SCOPE_AGENT); }
; #define XB_SPIN(cond, bar) do { unsigned _sp = 0; while (cond) { __builtin_amdgcn_s_sleep(1); \
;     if ((++_sp & 255u) == 0u) { if (xb_ld(&(bar)[XB_TMO])) break; if (_sp > XB_SPIN_CAP) { atomicAdd(&(bar)[XB_TMO], 1u); break; } } } } while (0)
; DI void xcd_barrier(const XcdBarrier& b) {
;     ...
;         const unsigned old = xb_add(&bar[XB_XSUB(b.x)], 1u);
;         const unsigned gen = old / nloc;
;         if (old + 1u == (gen + 1u) * nloc) {
;             __builtin_amdgcn_fence(__ATOMIC_RELEASE, "agent");
;             asm volatile("s_waitcnt vmcnt(0)" ::: "memory");
;             const unsigned og = xb_add(&bar[XB_TOP], 1u);
;             const unsigned tg = og / nx;
;             if (og + 1u == (tg + 1u) * nx) xb_add(&bar[XB_TOPGEN], 1u);
;             else XB_SPIN(xb_ld(&bar[XB_TOPGEN]) == tg, bar);
.LBB0_385:
	s_andn2_saveexec_b64 s[6:7], s[6:7]
	s_cbranch_execz .LBB0_405
	s_mov_b64 s[6:7], exec
	ds_read_b32 v3, v193 offset:8
	s_add_i32 s9, s52, -1
	s_waitcnt lgkmcnt(0)
	v_readfirstlane_b32 s8, v3
	s_cmp_lg_u32 s9, 0
	s_cselect_b32 s8, s8, 0
	s_cmp_lg_u32 s8, 0
	s_cbranch_scc1 .LBB0_402
	buffer_wbl2 sc1
	s_waitcnt lgkmcnt(0)
	s_waitcnt vmcnt(0)
	v_mbcnt_lo_u32_b32 v1, s6, 0
	v_mbcnt_hi_u32_b32 v1, s7, v1
	v_cmp_eq_u32_e32 vcc, 0, v1
	s_and_saveexec_b64 s[8:9], vcc
	s_cbranch_execz .LBB0_388
	s_bcnt1_i32_b64 s6, s[6:7]
	v_mov_b32_e32 v2, s6
	v_readlane_b32 s6, v255, 13
	v_readlane_b32 s7, v255, 14
	s_nop 4
	global_atomic_add v2, v193, v2, s[6:7] sc0
